# v079 + same epilogue store coalescing (ds_bpermute lane transpose) in P5 z|o GEMM, unpipelined
# speedup vs baseline: 1.0228x; 1.0043x over previous
; #define G_STAGE(bufoff, gbase, voff) do { _Pragma("unroll") for (int _i = 0; _i < 2; ++_i) \
;         __builtin_amdgcn_global_load_lds((const unsigned*)((const char*)(gbase) + (voff)[_i]), (LAS unsigned*)(lds + (bufoff) + ldsw + _i * 8192), 16, 0, 0); } while (0)
; #define G_WAIT_V(n) asm volatile("s_waitcnt vmcnt(" #n ")" ::: "memory")
; #define G_BAR __builtin_amdgcn_s_barrier()
; template <bool PERM, class Dec, class Epi>
; DI void gemm_phase(LAS unsigned char* lds, const int nM, const int nN, const int K, const int lda, const int ldb, const Dec& dec, const Epi& epi, const int vb, const int panel = -1) {
;     ...
;     G_STAGE(G_SB(0, 0), cB, voffB); G_STAGE(G_SA(0, 0), cA, voffA); G_STAGE(G_SB(0, 1), cB + hstepB, voffB); G_STAGE(G_SA(0, 1), cA + hstepA, voffA);
;     if (wr == 1) G_BAR;
;     G_WAIT_V(4); G_BAR;
;     G_STAGE(G_SB(1, 0), cB + kstep, voffB); G_STAGE(G_SA(1, 0), cA + kstep, voffA); G_STAGE(G_SB(1, 1), cB + hstepB + kstep, voffB);
;     G_WAIT_V(6); G_BAR;
; DI void epi_zo(const f32x4 (&acc)[2][2][4][2], unsigned char* O, const int esz, int wr, int wc, int fr, int fq) {
; #pragma unroll
;     for (int ai = 0; ai < 2; ++ai)
; #pragma unroll
;         for (int m = 0; m < 4; ++m) {
;             unsigned char* rowp = O + ((size_t)(ai * HALF + wr * 64 + m * 16 + fr) * 2048 + wc * 32 + 8 * fq) * esz;
.LBB0_478:
	v_lshrrev_b32_e32 v17, 1, v14
	v_and_b32_e32 v17, 24, v17
	v_and_b32_e32 v15, 15, v14
	v_lshlrev_b32_e32 v18, 1, v17
	v_lshlrev_b32_e32 v14, 2, v14
	v_bfe_u32 v16, v14, 4, 4
	v_lshl_or_b32 v16, s4, 6, v16
	v_lshl_or_b32 v15, v15, 6, v18
	s_lshl_b32 s3, s4, 13
	v_and_b32_e32 v14, 32, v14
	v_bitop3_b32 v18, v15, s3, v14 bitop3:0xde
	s_lshl_b32 s3, s5, 5
	s_and_b32 s3, s3, 0x60
	s_add_i32 m0, s35, 0x18000
	v_lshl_add_u64 v[6:7], v[6:7], 0, s[0:1]
	s_lshl_b32 s4, s3, 7
	s_waitcnt vmcnt(4)
	s_barrier
	global_load_lds_dwordx4 v[6:7], off
	v_lshl_add_u64 v[4:5], v[4:5], 0, s[0:1]
	s_add_i32 m0, s35, 0x1a000
	s_add_i32 s50, s35, 0x8000
	s_add_i32 s51, s35, 0xa000
	v_bitop3_b32 v165, v15, s4, v14 bitop3:0xde
	global_load_lds_dwordx4 v[4:5], off
	v_lshl_add_u64 v[2:3], v[2:3], 0, s[0:1]
	s_mov_b32 m0, s50
	s_add_u32 s4, s36, 0x40080
	global_load_lds_dwordx4 v[2:3], off
	v_lshl_add_u64 v[0:1], v[0:1], 0, s[0:1]
	s_mov_b32 m0, s51
	s_addc_u32 s5, s37, 0
	global_load_lds_dwordx4 v[0:1], off
	s_add_i32 m0, s35, 0x1c000
	v_lshl_add_u64 v[0:1], s[4:5], 0, v[128:129]
	global_load_lds_dwordx4 v[0:1], off
	v_lshl_add_u64 v[0:1], s[4:5], 0, v[138:139]
	s_add_i32 m0, s35, 0x1e000
	v_mbcnt_lo_u32_b32 v241, -1, 0
	v_mbcnt_hi_u32_b32 v241, -1, v241
	v_and_b32_e32 v240, 3, v241
	v_lshlrev_b32_e32 v240, 3, v240
	v_and_b32_e32 v241, 60, v241
	v_lshl_or_b32 v241, v240, 3, v241
	v_or_b32_e32 v2, s3, v240
	global_load_lds_dwordx4 v[0:1], off
	v_or_b32_e32 v0, 16, v16
	v_ashrrev_i32_e32 v1, 31, v0
	v_lshlrev_b64 v[142:143], 11, v[0:1]
	v_or_b32_e32 v0, 32, v16
	v_ashrrev_i32_e32 v1, 31, v0
	v_lshlrev_b64 v[144:145], 11, v[0:1]
	v_or_b32_e32 v0, 48, v16
	v_ashrrev_i32_e32 v1, 31, v0
	v_lshlrev_b64 v[146:147], 11, v[0:1]
	v_lshlrev_b32_e32 v0, 14, v8
	v_and_b32_e32 v0, 0xffff8000, v0
	v_ashrrev_i32_e32 v17, 31, v16
	v_lshl_add_u32 v0, v9, 11, v0
	v_and_b32_e32 v1, 1, v8
	v_lshlrev_b64 v[140:141], 11, v[16:17]
	v_lshl_or_b32 v0, v1, 6, v0
	v_or_b32_e32 v140, v140, v2
	s_mov_b64 s[4:5], 0x40000
	v_lshl_add_u32 v156, v10, 1, v0
	v_lshlrev_b32_e32 v0, 14, v11
	v_lshl_add_u64 v[148:149], v[140:141], 0, s[4:5]
	s_mov_b64 s[4:5], 0x48000
	v_and_b32_e32 v0, 0xffff8000, v0
	s_waitcnt vmcnt(6)
	v_lshl_add_u64 v[150:151], v[140:141], 0, s[4:5]
	s_mov_b64 s[4:5], 0x50000
	v_lshl_add_u32 v0, v12, 11, v0
	v_and_b32_e32 v1, 1, v11
	v_lshl_add_u64 v[152:153], v[140:141], 0, s[4:5]
	s_mov_b64 s[4:5], 0x58000
	v_lshl_or_b32 v0, v1, 6, v0
	v_or_b32_e32 v142, v142, v2
	v_or_b32_e32 v144, v144, v2
	v_or_b32_e32 v146, v146, v2
	v_lshl_add_u64 v[154:155], v[140:141], 0, s[4:5]
	v_mov_b32_e32 v157, v129
	v_lshl_add_u32 v158, v13, 1, v0
	v_mov_b32_e32 v159, v129
	s_mov_b32 s52, 0
	v_add_u32_e32 v166, 0, v18
	s_barrier
	s_waitcnt vmcnt(0)
	s_branch .LBB0_480

; #define G_STAGE(bufoff, gbase, voff) do { _Pragma("unroll") for (int _i = 0; _i < 2; ++_i) \
;         __builtin_amdgcn_global_load_lds((const unsigned*)((const char*)(gbase) + (voff)[_i]), (LAS unsigned*)(lds + (bufoff) + ldsw + _i * 8192), 16, 0, 0); } while (0)
; #define G_LDA(dst, b, h) do { _Pragma("unroll") for (int m = 0; m < 4; ++m) _Pragma("unroll") for (int k = 0; k < 2; ++k) dst[m][k] = *(const LAS bf16x8*)(lds + G_SA(b, h) + aoff + m * 2048 + k * 1024); } while (0)
; #define G_LDB(dst, b, h) do { _Pragma("unroll") for (int n = 0; n < 2; ++n) _Pragma("unroll") for (int k = 0; k < 2; ++k) dst[n][k] = *(const LAS bf16x8*)(lds + G_SB(b, h) + boff + n * 2048 + k * 1024); } while (0)
; #define G_MMA(ai, bj, At, Bt) do { __builtin_amdgcn_s_setprio(1); _Pragma("unroll") for (int m = 0; m < 4; ++m) _Pragma("unroll") for (int n = 0; n < 2; ++n) _Pragma("unroll") for (int k = 0; k < 2; ++k) \
;         acc[ai][bj][m][n] = __builtin_amdgcn_mfma_f32_16x16x32_bf16(Bt[n][k], At[m][k], acc[ai][bj][m][n], 0, 0, 0); __builtin_amdgcn_s_setprio(0); } while (0)
; #define G_WAIT_V(n) asm volatile("s_waitcnt vmcnt(" #n ")" ::: "memory")
; #define G_WAIT_L(n) asm volatile("s_waitcnt lgkmcnt(" #n ")" ::: "memory")
; #define G_BAR __builtin_amdgcn_s_barrier()
; #define G_SCHED __builtin_amdgcn_sched_barrier(0)
; template <bool PERM, class Dec, class Epi>
; DI void gemm_phase(LAS unsigned char* lds, const int nM, const int nN, const int K, const int lda, const int ldb, const Dec& dec, const Epi& epi, const int vb, const int panel = -1) {
;     ...
;             G_LDB(B0, 0, 0); G_SCHED; G_LDA(At, 0, 0); G_STAGE(G_SA(1, 1), a1 + hstepA, voffA);
;             G_WAIT_L(8); G_BAR; G_WAIT_L(0); G_MMA(0, 0, At, B0); G_BAR; G_SCHED;
;             G_LDB(B1, 0, 1); G_STAGE(G_SB(0, 0), b2, voffB);
;             G_BAR; G_WAIT_L(0); G_MMA(0, 1, At, B1); G_BAR;
;             G_LDA(At, 0, 1); G_STAGE(G_SA(0, 0), a2, voffA);
;             G_BAR; G_WAIT_L(0); G_MMA(1, 0, At, B0); G_BAR; G_SCHED;
;             G_STAGE(G_SB(0, 1), b2 + hstepB, voffB);
;             G_WAIT_V(6); G_BAR; G_MMA(1, 1, At, B1); G_BAR;
.LBB0_483:
	s_add_u32 s36, s22, 0xfffc0080
	s_addc_u32 s37, s23, -1
	s_add_i32 s57, 0, 0x10000
	v_add_u32_e32 v167, s57, v165
	ds_read_b128 v[160:163], v167
	ds_read_b128 v[172:175], v167 offset:1024
	ds_read_b128 v[176:179], v167 offset:2048
	ds_read_b128 v[180:183], v167 offset:3072
	s_cmp_eq_u32 s56, 12
	s_cselect_b32 s45, s3, s37
	s_cselect_b32 s44, s5, s36
	s_cselect_b32 s37, s7, s55
	s_cselect_b32 s36, s53, s54
	v_lshl_add_u64 v[168:169], s[22:23], 0, v[156:157]
	s_add_i32 m0, s35, 0xc000
	ds_read_b128 v[184:187], v166
	ds_read_b128 v[188:191], v166 offset:1024
	ds_read_b128 v[194:197], v166 offset:2048
	ds_read_b128 v[198:201], v166 offset:3072
	ds_read_b128 v[202:205], v166 offset:4096
	ds_read_b128 v[206:209], v166 offset:5120
	ds_read_b128 v[210:213], v166 offset:6144
	ds_read_b128 v[214:217], v166 offset:7168
	global_load_lds_dwordx4 v[168:169], off
	v_lshl_add_u64 v[168:169], s[22:23], 0, v[158:159]
	s_add_i32 m0, s35, 0xe000
	s_nop 0
	global_load_lds_dwordx4 v[168:169], off
	s_waitcnt lgkmcnt(8)
	s_barrier
	s_waitcnt lgkmcnt(0)
	s_setprio 1
	s_waitcnt lgkmcnt(0)
	v_mfma_f32_16x16x32_bf16 v[124:127], v[160:163], v[184:187], v[124:127]
	v_mfma_f32_16x16x32_bf16 v[120:123], v[176:179], v[184:187], v[120:123]
	v_mfma_f32_16x16x32_bf16 v[108:111], v[160:163], v[194:197], v[108:111]
	v_mfma_f32_16x16x32_bf16 v[104:107], v[176:179], v[194:197], v[104:107]
	v_mfma_f32_16x16x32_bf16 v[92:95], v[160:163], v[202:205], v[92:95]
	v_mfma_f32_16x16x32_bf16 v[88:91], v[176:179], v[202:205], v[88:91]
	v_mfma_f32_16x16x32_bf16 v[76:79], v[160:163], v[210:213], v[76:79]
	v_mfma_f32_16x16x32_bf16 v[72:75], v[176:179], v[210:213], v[72:75]
	v_mfma_f32_16x16x32_bf16 v[124:127], v[172:175], v[188:191], v[124:127]
	v_mfma_f32_16x16x32_bf16 v[120:123], v[180:183], v[188:191], v[120:123]
	v_mfma_f32_16x16x32_bf16 v[108:111], v[172:175], v[198:201], v[108:111]
	v_mfma_f32_16x16x32_bf16 v[104:107], v[180:183], v[198:201], v[104:107]
	v_mfma_f32_16x16x32_bf16 v[92:95], v[172:175], v[206:209], v[92:95]
	v_mfma_f32_16x16x32_bf16 v[88:91], v[180:183], v[206:209], v[88:91]
	v_mfma_f32_16x16x32_bf16 v[76:79], v[172:175], v[214:217], v[76:79]
	v_mfma_f32_16x16x32_bf16 v[72:75], v[180:183], v[214:217], v[72:75]
	s_setprio 0
	s_barrier
	s_add_i32 s60, 0, 0x14000
	s_add_i32 s57, s57, s46
	v_add_u32_e32 v167, s60, v165
	v_lshl_add_u64 v[168:169], s[36:37], 0, v[128:129]
	s_mov_b32 m0, s57
	ds_read_b128 v[218:221], v167
	ds_read_b128 v[222:225], v167 offset:1024
	ds_read_b128 v[226:229], v167 offset:2048
	ds_read_b128 v[230:233], v167 offset:3072
	global_load_lds_dwordx4 v[168:169], off
	v_lshl_add_u64 v[234:235], s[36:37], 0, v[138:139]
	s_add_i32 m0, s57, 0x2000
	s_nop 0
	global_load_lds_dwordx4 v[234:235], off
	s_barrier
	s_waitcnt lgkmcnt(0)
	s_setprio 1
	s_waitcnt lgkmcnt(0)
	v_mfma_f32_16x16x32_bf16 v[116:119], v[218:221], v[184:187], v[116:119]
	v_mfma_f32_16x16x32_bf16 v[112:115], v[226:229], v[184:187], v[112:115]
	v_mfma_f32_16x16x32_bf16 v[100:103], v[218:221], v[194:197], v[100:103]
	v_mfma_f32_16x16x32_bf16 v[96:99], v[226:229], v[194:197], v[96:99]
	v_mfma_f32_16x16x32_bf16 v[84:87], v[218:221], v[202:205], v[84:87]
	v_mfma_f32_16x16x32_bf16 v[80:83], v[226:229], v[202:205], v[80:83]
	v_mfma_f32_16x16x32_bf16 v[68:71], v[218:221], v[210:213], v[68:71]
	v_mfma_f32_16x16x32_bf16 v[64:67], v[226:229], v[210:213], v[64:67]
	v_mfma_f32_16x16x32_bf16 v[116:119], v[222:225], v[188:191], v[116:119]
	v_mfma_f32_16x16x32_bf16 v[112:115], v[230:233], v[188:191], v[112:115]
	v_mfma_f32_16x16x32_bf16 v[100:103], v[222:225], v[198:201], v[100:103]
	v_mfma_f32_16x16x32_bf16 v[96:99], v[230:233], v[198:201], v[96:99]
	v_mfma_f32_16x16x32_bf16 v[84:87], v[222:225], v[206:209], v[84:87]
	v_mfma_f32_16x16x32_bf16 v[80:83], v[230:233], v[206:209], v[80:83]
	v_mfma_f32_16x16x32_bf16 v[68:71], v[222:225], v[214:217], v[68:71]
	v_mfma_f32_16x16x32_bf16 v[64:67], v[230:233], v[214:217], v[64:67]
	s_setprio 0
	s_mov_b32 m0, s35
	v_lshl_add_u64 v[236:237], s[44:45], 0, v[134:135]
	s_barrier
	ds_read_b128 v[184:187], v166 offset:16384
	ds_read_b128 v[188:191], v166 offset:17408
	ds_read_b128 v[194:197], v166 offset:18432
	ds_read_b128 v[198:201], v166 offset:19456
	ds_read_b128 v[202:205], v166 offset:20480
	ds_read_b128 v[206:209], v166 offset:21504
	ds_read_b128 v[210:213], v166 offset:22528
	ds_read_b128 v[214:217], v166 offset:23552
	global_load_lds_dwordx4 v[236:237], off
	v_lshl_add_u64 v[238:239], s[44:45], 0, v[136:137]
	s_mov_b32 m0, s47
	s_nop 0
	global_load_lds_dwordx4 v[238:239], off
	s_barrier
	s_waitcnt lgkmcnt(0)
	s_setprio 1
	s_waitcnt lgkmcnt(0)
	v_mfma_f32_16x16x32_bf16 v[60:63], v[160:163], v[184:187], v[60:63]
	v_mfma_f32_16x16x32_bf16 v[56:59], v[176:179], v[184:187], v[56:59]
	v_mfma_f32_16x16x32_bf16 v[44:47], v[160:163], v[194:197], v[44:47]
	v_mfma_f32_16x16x32_bf16 v[40:43], v[176:179], v[194:197], v[40:43]
	v_mfma_f32_16x16x32_bf16 v[28:31], v[160:163], v[202:205], v[28:31]
	v_mfma_f32_16x16x32_bf16 v[24:27], v[176:179], v[202:205], v[24:27]
	v_mfma_f32_16x16x32_bf16 v[12:15], v[160:163], v[210:213], v[12:15]
	v_mfma_f32_16x16x32_bf16 v[8:11], v[176:179], v[210:213], v[8:11]
	v_mfma_f32_16x16x32_bf16 v[60:63], v[172:175], v[188:191], v[60:63]
	v_mfma_f32_16x16x32_bf16 v[56:59], v[180:183], v[188:191], v[56:59]
	v_mfma_f32_16x16x32_bf16 v[44:47], v[172:175], v[198:201], v[44:47]
	v_mfma_f32_16x16x32_bf16 v[40:43], v[180:183], v[198:201], v[40:43]
	v_mfma_f32_16x16x32_bf16 v[28:31], v[172:175], v[206:209], v[28:31]
	v_mfma_f32_16x16x32_bf16 v[24:27], v[180:183], v[206:209], v[24:27]
	v_mfma_f32_16x16x32_bf16 v[12:15], v[172:175], v[214:217], v[12:15]
	v_mfma_f32_16x16x32_bf16 v[8:11], v[180:183], v[214:217], v[8:11]
	s_setprio 0
	s_barrier
; #define G_STAGE(bufoff, gbase, voff) do { _Pragma("unroll") for (int _i = 0; _i < 2; ++_i) \
;         __builtin_amdgcn_global_load_lds((const unsigned*)((const char*)(gbase) + (voff)[_i]), (LAS unsigned*)(lds + (bufoff) + ldsw + _i * 8192), 16, 0, 0); } while (0)
; #define G_LDA(dst, b, h) do { _Pragma("unroll") for (int m = 0; m < 4; ++m) _Pragma("unroll") for (int k = 0; k < 2; ++k) dst[m][k] = *(const LAS bf16x8*)(lds + G_SA(b, h) + aoff + m * 2048 + k * 1024); } while (0)
; #define G_LDB(dst, b, h) do { _Pragma("unroll") for (int n = 0; n < 2; ++n) _Pragma("unroll") for (int k = 0; k < 2; ++k) dst[n][k] = *(const LAS bf16x8*)(lds + G_SB(b, h) + boff + n * 2048 + k * 1024); } while (0)
; #define G_MMA(ai, bj, At, Bt) do { __builtin_amdgcn_s_setprio(1); _Pragma("unroll") for (int m = 0; m < 4; ++m) _Pragma("unroll") for (int n = 0; n < 2; ++n) _Pragma("unroll") for (int k = 0; k < 2; ++k) \
;         acc[ai][bj][m][n] = __builtin_amdgcn_mfma_f32_16x16x32_bf16(Bt[n][k], At[m][k], acc[ai][bj][m][n], 0, 0, 0); __builtin_amdgcn_s_setprio(0); } while (0)
; #define G_WAIT_V(n) asm volatile("s_waitcnt vmcnt(" #n ")" ::: "memory")
; #define G_WAIT_L(n) asm volatile("s_waitcnt lgkmcnt(" #n ")" ::: "memory")
; #define G_BAR __builtin_amdgcn_s_barrier()
; #define G_SCHED __builtin_amdgcn_sched_barrier(0)
; template <bool PERM, class Dec, class Epi>
; DI void gemm_phase(LAS unsigned char* lds, const int nM, const int nN, const int K, const int lda, const int ldb, const Dec& dec, const Epi& epi, const int vb, const int panel = -1) {
;     ...
;             G_WAIT_V(6); G_BAR; G_MMA(1, 1, At, B1); G_BAR;
;             G_LDB(B0, 1, 0); G_SCHED; G_LDA(At, 1, 0); G_STAGE(G_SA(0, 1), a2 + hstepA, voffA);
;             G_WAIT_L(8); G_BAR; G_WAIT_L(0); G_MMA(0, 0, At, B0); G_BAR; G_SCHED;
;             G_LDB(B1, 1, 1); G_STAGE(G_SB(1, 0), b3, voffB);
;             G_BAR; G_WAIT_L(0); G_MMA(0, 1, At, B1); G_BAR;
;             G_LDA(At, 1, 1); G_STAGE(G_SA(1, 0), a3, voffA);
;             G_BAR; G_WAIT_L(0); G_MMA(1, 0, At, B0); G_BAR; G_SCHED;
	s_add_u32 s58, s36, 0x40000
	s_addc_u32 s59, s37, 0
	s_add_i32 s57, s60, s46
	v_lshl_add_u64 v[160:161], s[58:59], 0, v[128:129]
	s_mov_b32 m0, s57
	s_nop 0
	global_load_lds_dwordx4 v[160:161], off
	v_lshl_add_u64 v[160:161], s[58:59], 0, v[138:139]
	s_add_i32 m0, s57, 0x2000
	s_nop 0
	global_load_lds_dwordx4 v[160:161], off
	s_waitcnt vmcnt(6)
	s_barrier
	s_setprio 1
	v_mfma_f32_16x16x32_bf16 v[52:55], v[218:221], v[184:187], v[52:55]
	v_mfma_f32_16x16x32_bf16 v[48:51], v[226:229], v[184:187], v[48:51]
	v_mfma_f32_16x16x32_bf16 v[36:39], v[218:221], v[194:197], v[36:39]
	v_mfma_f32_16x16x32_bf16 v[32:35], v[226:229], v[194:197], v[32:35]
	v_mfma_f32_16x16x32_bf16 v[20:23], v[218:221], v[202:205], v[20:23]
	v_mfma_f32_16x16x32_bf16 v[16:19], v[226:229], v[202:205], v[16:19]
	v_mfma_f32_16x16x32_bf16 v[4:7], v[218:221], v[210:213], v[4:7]
	v_mfma_f32_16x16x32_bf16 v[0:3], v[226:229], v[210:213], v[0:3]
	v_mfma_f32_16x16x32_bf16 v[52:55], v[222:225], v[188:191], v[52:55]
	v_mfma_f32_16x16x32_bf16 v[48:51], v[230:233], v[188:191], v[48:51]
	v_mfma_f32_16x16x32_bf16 v[36:39], v[222:225], v[198:201], v[36:39]
	v_mfma_f32_16x16x32_bf16 v[32:35], v[230:233], v[198:201], v[32:35]
	v_mfma_f32_16x16x32_bf16 v[20:23], v[222:225], v[206:209], v[20:23]
	v_mfma_f32_16x16x32_bf16 v[16:19], v[230:233], v[206:209], v[16:19]
	v_mfma_f32_16x16x32_bf16 v[4:7], v[222:225], v[214:217], v[4:7]
	v_mfma_f32_16x16x32_bf16 v[0:3], v[230:233], v[214:217], v[0:3]
	s_setprio 0
	s_add_i32 s57, 0, 0x18000
	v_add_u32_e32 v167, s57, v165
	s_barrier
	ds_read_b128 v[160:163], v167
	ds_read_b128 v[172:175], v167 offset:1024
	ds_read_b128 v[176:179], v167 offset:2048
	ds_read_b128 v[180:183], v167 offset:3072
	s_add_u32 s44, s44, 0x40000
	s_addc_u32 s45, s45, 0
	s_mov_b32 m0, s48
	v_lshl_add_u64 v[218:219], s[44:45], 0, v[134:135]
	ds_read_b128 v[184:187], v166 offset:32768
	ds_read_b128 v[188:191], v166 offset:33792
	ds_read_b128 v[194:197], v166 offset:34816
	ds_read_b128 v[198:201], v166 offset:35840
	ds_read_b128 v[202:205], v166 offset:36864
	ds_read_b128 v[206:209], v166 offset:37888
	ds_read_b128 v[210:213], v166 offset:38912
	ds_read_b128 v[214:217], v166 offset:39936
	global_load_lds_dwordx4 v[218:219], off
	v_lshl_add_u64 v[218:219], s[44:45], 0, v[136:137]
	s_mov_b32 m0, s49
	s_nop 0
	global_load_lds_dwordx4 v[218:219], off
	s_waitcnt lgkmcnt(8)
	s_barrier
	s_waitcnt lgkmcnt(0)
	s_setprio 1
	s_waitcnt lgkmcnt(0)
	v_mfma_f32_16x16x32_bf16 v[124:127], v[160:163], v[184:187], v[124:127]
	v_mfma_f32_16x16x32_bf16 v[120:123], v[176:179], v[184:187], v[120:123]
	v_mfma_f32_16x16x32_bf16 v[108:111], v[160:163], v[194:197], v[108:111]
	v_mfma_f32_16x16x32_bf16 v[104:107], v[176:179], v[194:197], v[104:107]
	v_mfma_f32_16x16x32_bf16 v[92:95], v[160:163], v[202:205], v[92:95]
	v_mfma_f32_16x16x32_bf16 v[88:91], v[176:179], v[202:205], v[88:91]
	v_mfma_f32_16x16x32_bf16 v[76:79], v[160:163], v[210:213], v[76:79]
	v_mfma_f32_16x16x32_bf16 v[72:75], v[176:179], v[210:213], v[72:75]
	v_mfma_f32_16x16x32_bf16 v[124:127], v[172:175], v[188:191], v[124:127]
	v_mfma_f32_16x16x32_bf16 v[120:123], v[180:183], v[188:191], v[120:123]
	v_mfma_f32_16x16x32_bf16 v[108:111], v[172:175], v[198:201], v[108:111]
	v_mfma_f32_16x16x32_bf16 v[104:107], v[180:183], v[198:201], v[104:107]
	v_mfma_f32_16x16x32_bf16 v[92:95], v[172:175], v[206:209], v[92:95]
	v_mfma_f32_16x16x32_bf16 v[88:91], v[180:183], v[206:209], v[88:91]
	v_mfma_f32_16x16x32_bf16 v[76:79], v[172:175], v[214:217], v[76:79]
	v_mfma_f32_16x16x32_bf16 v[72:75], v[180:183], v[214:217], v[72:75]
	s_setprio 0
	s_barrier
	s_add_i32 s44, 0, 0x1c000
	s_add_i32 s45, s57, s46
	v_add_u32_e32 v167, s44, v165
	v_lshl_add_u64 v[168:169], v[168:169], 0, s[0:1]
	s_mov_b32 m0, s45
	ds_read_b128 v[218:221], v167
	ds_read_b128 v[222:225], v167 offset:1024
	ds_read_b128 v[226:229], v167 offset:2048
	ds_read_b128 v[230:233], v167 offset:3072
	global_load_lds_dwordx4 v[168:169], off
	v_lshl_add_u64 v[168:169], v[234:235], 0, s[0:1]
	s_add_i32 m0, s45, 0x2000
	s_nop 0
	global_load_lds_dwordx4 v[168:169], off
	s_barrier
	s_waitcnt lgkmcnt(0)
	s_setprio 1
	s_waitcnt lgkmcnt(0)
	v_mfma_f32_16x16x32_bf16 v[116:119], v[218:221], v[184:187], v[116:119]
	v_mfma_f32_16x16x32_bf16 v[112:115], v[226:229], v[184:187], v[112:115]
	v_mfma_f32_16x16x32_bf16 v[100:103], v[218:221], v[194:197], v[100:103]
	v_mfma_f32_16x16x32_bf16 v[96:99], v[226:229], v[194:197], v[96:99]
	v_mfma_f32_16x16x32_bf16 v[84:87], v[218:221], v[202:205], v[84:87]
	v_mfma_f32_16x16x32_bf16 v[80:83], v[226:229], v[202:205], v[80:83]
	v_mfma_f32_16x16x32_bf16 v[68:71], v[218:221], v[210:213], v[68:71]
	v_mfma_f32_16x16x32_bf16 v[64:67], v[226:229], v[210:213], v[64:67]
	v_mfma_f32_16x16x32_bf16 v[116:119], v[222:225], v[188:191], v[116:119]
	v_mfma_f32_16x16x32_bf16 v[112:115], v[230:233], v[188:191], v[112:115]
	v_mfma_f32_16x16x32_bf16 v[100:103], v[222:225], v[198:201], v[100:103]
	v_mfma_f32_16x16x32_bf16 v[96:99], v[230:233], v[198:201], v[96:99]
	v_mfma_f32_16x16x32_bf16 v[84:87], v[222:225], v[206:209], v[84:87]
	v_mfma_f32_16x16x32_bf16 v[80:83], v[230:233], v[206:209], v[80:83]
	v_mfma_f32_16x16x32_bf16 v[68:71], v[222:225], v[214:217], v[68:71]
	v_mfma_f32_16x16x32_bf16 v[64:67], v[230:233], v[214:217], v[64:67]
	s_setprio 0
	s_mov_b32 m0, s50
	v_lshl_add_u64 v[168:169], v[236:237], 0, s[0:1]
	s_barrier
	ds_read_b128 v[184:187], v166 offset:49152
	ds_read_b128 v[188:191], v166 offset:50176
	ds_read_b128 v[194:197], v166 offset:51200
	ds_read_b128 v[198:201], v166 offset:52224
	ds_read_b128 v[202:205], v166 offset:53248
	ds_read_b128 v[206:209], v166 offset:54272
	ds_read_b128 v[210:213], v166 offset:55296
	ds_read_b128 v[214:217], v166 offset:56320
	global_load_lds_dwordx4 v[168:169], off
	v_lshl_add_u64 v[168:169], v[238:239], 0, s[0:1]
	s_mov_b32 m0, s51
	s_nop 0
	global_load_lds_dwordx4 v[168:169], off
	s_barrier
; DI unsigned pk2(float a, float b) { f32x2 v = {a, b}; bf2_t r = __builtin_convertvector(v, bf2_t); return __builtin_bit_cast(unsigned, r); }
; DI unsigned pk_fp8x4(float a, float b, float c, float d) { int w = __builtin_amdgcn_cvt_pk_fp8_f32(a, b, 0, false); w = __builtin_amdgcn_cvt_pk_fp8_f32(c, d, w, true); return (unsigned)w; }
; #define G_STAGE(bufoff, gbase, voff) do { _Pragma("unroll") for (int _i = 0; _i < 2; ++_i) \
;         __builtin_amdgcn_global_load_lds((const unsigned*)((const char*)(gbase) + (voff)[_i]), (LAS unsigned*)(lds + (bufoff) + ldsw + _i * 8192), 16, 0, 0); } while (0)
; #define G_MMA(ai, bj, At, Bt) do { __builtin_amdgcn_s_setprio(1); _Pragma("unroll") for (int m = 0; m < 4; ++m) _Pragma("unroll") for (int n = 0; n < 2; ++n) _Pragma("unroll") for (int k = 0; k < 2; ++k) \
;         acc[ai][bj][m][n] = __builtin_amdgcn_mfma_f32_16x16x32_bf16(Bt[n][k], At[m][k], acc[ai][bj][m][n], 0, 0, 0); __builtin_amdgcn_s_setprio(0); } while (0)
; #define G_WAIT_V(n) asm volatile("s_waitcnt vmcnt(" #n ")" ::: "memory")
; #define G_BAR __builtin_amdgcn_s_barrier()
; template <bool PERM, class Dec, class Epi>
; DI void gemm_phase(LAS unsigned char* lds, const int nM, const int nN, const int K, const int lda, const int ldb, const Dec& dec, const Epi& epi, const int vb, const int panel = -1) {
;     ...
;             G_BAR; G_WAIT_L(0); G_MMA(1, 0, At, B0); G_BAR; G_SCHED;
;             G_STAGE(G_SB(1, 1), b3 + hstepB, voffB);
;             G_WAIT_V(6); G_BAR; G_MMA(1, 1, At, B1); G_BAR;
;         }
; DI void epi_zo(const f32x4 (&acc)[2][2][4][2], unsigned char* O, const int esz, int wr, int wc, int fr, int fq) {
; #pragma unroll
;     for (int ai = 0; ai < 2; ++ai)
; #pragma unroll
;         for (int m = 0; m < 4; ++m) {
;             unsigned char* rowp = O + ((size_t)(ai * HALF + wr * 64 + m * 16 + fr) * 2048 + wc * 32 + 8 * fq) * esz;
; #pragma unroll
;             for (int bj = 0; bj < 2; ++bj) {
;                 const f32x4 v0 = acc[ai][bj][m][0], v1 = acc[ai][bj][m][1];
;                 if (esz == 2) { u32x4 w; w[0] = pk2(v0[0], v0[1]); w[1] = pk2(v0[2], v0[3]); w[2] = pk2(v1[0], v1[1]); w[3] = pk2(v1[2], v1[3]); *(u32x4*)(rowp + bj * HALF * 2) = w; }
;                 else { u32x2 w; w[0] = pk_fp8x4(v0[0], v0[1], v0[2], v0[3]); w[1] = pk_fp8x4(v1[0], v1[1], v1[2], v1[3]); *(u32x2*)(rowp + bj * HALF) = w; }
;             }
	s_waitcnt lgkmcnt(0)
	s_setprio 1
	s_waitcnt lgkmcnt(0)
	v_mfma_f32_16x16x32_bf16 v[60:63], v[160:163], v[184:187], v[60:63]
	v_mfma_f32_16x16x32_bf16 v[56:59], v[176:179], v[184:187], v[56:59]
	v_mfma_f32_16x16x32_bf16 v[44:47], v[160:163], v[194:197], v[44:47]
	v_mfma_f32_16x16x32_bf16 v[40:43], v[176:179], v[194:197], v[40:43]
	v_mfma_f32_16x16x32_bf16 v[28:31], v[160:163], v[202:205], v[28:31]
	v_mfma_f32_16x16x32_bf16 v[24:27], v[176:179], v[202:205], v[24:27]
	v_mfma_f32_16x16x32_bf16 v[12:15], v[160:163], v[210:213], v[12:15]
	v_mfma_f32_16x16x32_bf16 v[8:11], v[176:179], v[210:213], v[8:11]
	v_mfma_f32_16x16x32_bf16 v[60:63], v[172:175], v[188:191], v[60:63]
	v_mfma_f32_16x16x32_bf16 v[56:59], v[180:183], v[188:191], v[56:59]
	v_mfma_f32_16x16x32_bf16 v[44:47], v[172:175], v[198:201], v[44:47]
	v_mfma_f32_16x16x32_bf16 v[40:43], v[180:183], v[198:201], v[40:43]
	v_mfma_f32_16x16x32_bf16 v[28:31], v[172:175], v[206:209], v[28:31]
	v_mfma_f32_16x16x32_bf16 v[24:27], v[180:183], v[206:209], v[24:27]
	v_mfma_f32_16x16x32_bf16 v[12:15], v[172:175], v[214:217], v[12:15]
	v_mfma_f32_16x16x32_bf16 v[8:11], v[180:183], v[214:217], v[8:11]
	s_setprio 0
	s_barrier
	s_add_u32 s36, s36, 0x40080
	s_addc_u32 s37, s37, 0
	s_add_i32 s44, s44, s46
	v_lshl_add_u64 v[160:161], s[36:37], 0, v[128:129]
	s_mov_b32 m0, s44
	s_nop 0
	global_load_lds_dwordx4 v[160:161], off
	v_lshl_add_u64 v[160:161], s[36:37], 0, v[138:139]
	s_add_i32 m0, s44, 0x2000
	s_nop 0
	global_load_lds_dwordx4 v[160:161], off
	s_waitcnt vmcnt(6)
	s_barrier
	s_setprio 1
	v_mfma_f32_16x16x32_bf16 v[52:55], v[218:221], v[184:187], v[52:55]
	v_mfma_f32_16x16x32_bf16 v[48:51], v[226:229], v[184:187], v[48:51]
	v_mfma_f32_16x16x32_bf16 v[36:39], v[218:221], v[194:197], v[36:39]
	v_mfma_f32_16x16x32_bf16 v[32:35], v[226:229], v[194:197], v[32:35]
	v_mfma_f32_16x16x32_bf16 v[20:23], v[218:221], v[202:205], v[20:23]
	v_mfma_f32_16x16x32_bf16 v[16:19], v[226:229], v[202:205], v[16:19]
	v_mfma_f32_16x16x32_bf16 v[4:7], v[218:221], v[210:213], v[4:7]
	v_mfma_f32_16x16x32_bf16 v[0:3], v[226:229], v[210:213], v[0:3]
	v_mfma_f32_16x16x32_bf16 v[52:55], v[222:225], v[188:191], v[52:55]
	v_mfma_f32_16x16x32_bf16 v[48:51], v[230:233], v[188:191], v[48:51]
	v_mfma_f32_16x16x32_bf16 v[36:39], v[222:225], v[198:201], v[36:39]
	v_mfma_f32_16x16x32_bf16 v[32:35], v[230:233], v[198:201], v[32:35]
	v_mfma_f32_16x16x32_bf16 v[20:23], v[222:225], v[206:209], v[20:23]
	v_mfma_f32_16x16x32_bf16 v[16:19], v[230:233], v[206:209], v[16:19]
	v_mfma_f32_16x16x32_bf16 v[4:7], v[222:225], v[214:217], v[4:7]
	v_mfma_f32_16x16x32_bf16 v[0:3], v[230:233], v[214:217], v[0:3]
	s_setprio 0
	s_add_i32 s56, s56, 2
	s_add_u32 s22, s22, 0x100
	s_addc_u32 s23, s23, 0
	s_add_u32 s54, s54, 0x100
	s_addc_u32 s55, s55, 0
	s_cmp_gt_u32 s56, 13
	s_barrier
	s_cbranch_scc0 .LBB0_483
	s_cmp_gt_i32 s34, 7
	s_cselect_b64 s[22:23], -1, 0
	s_cmp_lt_i32 s34, 8
	s_cselect_b64 s[36:37], -1, 0
	v_cndmask_b32_e64 v167, 0, 1, s[36:37]
	s_and_b64 s[36:37], s[36:37], exec
	s_cselect_b32 s37, s17, s95
	s_cselect_b32 s36, s16, s94
	s_ashr_i32 s3, s2, 31
	s_lshl_b32 s5, s34, 8
	s_lshl_b64 s[2:3], s[2:3], 19
	s_and_b32 s5, s5, 0x700
	s_or_b32 s2, s2, s5
	v_lshlrev_b64 v[160:161], v167, s[2:3]
	v_lshl_add_u64 v[160:161], s[36:37], 0, v[160:161]
	v_lshlrev_b64 v[162:163], v167, v[140:141]
	v_lshl_add_u64 v[162:163], v[160:161], 0, v[162:163]
	s_mov_b64 s[2:3], -1
	s_and_b64 vcc, exec, s[22:23]
	s_cbranch_vccz .LBB0_486
	v_mov_b32_e32 v168, 0
	v_mov_b32_e32 v169, 0
	v_cvt_pk_fp8_f32 v168, v124, v125
	v_cvt_pk_fp8_f32 v169, v120, v121
	s_mov_b64 s[2:3], 0
	v_cvt_pk_fp8_f32 v168, v126, v127 op_sel:[0,0,1]
	v_cvt_pk_fp8_f32 v169, v122, v123 op_sel:[0,0,1]
	ds_bpermute_b32 v168, v241, v168
	ds_bpermute_b32 v169, v241, v169
	s_waitcnt lgkmcnt(0)
	global_store_dwordx2 v[162:163], v[168:169], off
.LBB0_486:
	s_andn2_b64 vcc, exec, s[2:3]
	s_cbranch_vccnz .LBB0_488
	v_cvt_pk_bf16_f32 v124, v124, v125
	v_cvt_pk_bf16_f32 v125, v126, v127
	v_cvt_pk_bf16_f32 v126, v120, v121
	v_cvt_pk_bf16_f32 v127, v122, v123
	ds_bpermute_b32 v124, v241, v124
	ds_bpermute_b32 v125, v241, v125
	ds_bpermute_b32 v126, v241, v126
	ds_bpermute_b32 v127, v241, v127
	s_waitcnt lgkmcnt(0)
	global_store_dwordx4 v[162:163], v[124:127], off
.LBB0_488:
	v_cndmask_b32_e64 v120, 0, 1, s[22:23]
	v_cmp_ne_u32_e64 s[44:45], 1, v120
	s_andn2_b64 vcc, exec, s[22:23]
	s_mov_b64 s[2:3], -1
	s_cbranch_vccnz .LBB0_490
	v_mov_b32_e32 v120, 0
	v_mov_b32_e32 v121, 0
	v_cvt_pk_fp8_f32 v120, v116, v117
	v_cvt_pk_fp8_f32 v121, v112, v113
	s_mov_b64 s[2:3], 0
	v_cvt_pk_fp8_f32 v120, v118, v119 op_sel:[0,0,1]
	v_cvt_pk_fp8_f32 v121, v114, v115 op_sel:[0,0,1]
	ds_bpermute_b32 v120, v241, v120
	ds_bpermute_b32 v121, v241, v121
	s_waitcnt lgkmcnt(0)
	global_store_dwordx2 v[162:163], v[120:121], off offset:128
.LBB0_490:
	s_andn2_b64 vcc, exec, s[2:3]
	s_cbranch_vccnz .LBB0_492
	v_cvt_pk_bf16_f32 v116, v116, v117
	v_cvt_pk_bf16_f32 v117, v118, v119
	v_cvt_pk_bf16_f32 v118, v112, v113
	v_cvt_pk_bf16_f32 v119, v114, v115
	ds_bpermute_b32 v116, v241, v116
	ds_bpermute_b32 v117, v241, v117
	ds_bpermute_b32 v118, v241, v118
	ds_bpermute_b32 v119, v241, v119
	s_waitcnt lgkmcnt(0)
	global_store_dwordx4 v[162:163], v[116:119], off offset:256
.LBB0_492:
	v_lshlrev_b64 v[112:113], v167, v[142:143]
	v_lshl_add_u64 v[112:113], v[160:161], 0, v[112:113]
	s_and_b64 vcc, exec, s[44:45]
	s_mov_b64 s[2:3], -1
	s_cbranch_vccnz .LBB0_496
	v_mov_b32_e32 v114, 0
	v_mov_b32_e32 v115, 0
	v_cvt_pk_fp8_f32 v114, v108, v109
	v_cvt_pk_fp8_f32 v115, v104, v105
	v_cvt_pk_fp8_f32 v114, v110, v111 op_sel:[0,0,1]
	v_cvt_pk_fp8_f32 v115, v106, v107 op_sel:[0,0,1]
	ds_bpermute_b32 v114, v241, v114
	ds_bpermute_b32 v115, v241, v115
	s_waitcnt lgkmcnt(0)
	global_store_dwordx2 v[112:113], v[114:115], off
	s_cbranch_execz .LBB0_497

; DI unsigned pk_fp8x4(float a, float b, float c, float d) { int w = __builtin_amdgcn_cvt_pk_fp8_f32(a, b, 0, false); w = __builtin_amdgcn_cvt_pk_fp8_f32(c, d, w, true); return (unsigned)w; }
; DI void epi_zo(const f32x4 (&acc)[2][2][4][2], unsigned char* O, const int esz, int wr, int wc, int fr, int fq) {
;     ...
;                 else { u32x2 w; w[0] = pk_fp8x4(v0[0], v0[1], v0[2], v0[3]); w[1] = pk_fp8x4(v1[0], v1[1], v1[2], v1[3]); *(u32x2*)(rowp + bj * HALF) = w; }
.LBB0_495:
	v_mov_b32_e32 v104, 0
	v_mov_b32_e32 v105, 0
	v_cvt_pk_fp8_f32 v104, v100, v101
	v_cvt_pk_fp8_f32 v105, v96, v97
	v_cvt_pk_fp8_f32 v104, v102, v103 op_sel:[0,0,1]
	v_cvt_pk_fp8_f32 v105, v98, v99 op_sel:[0,0,1]
	ds_bpermute_b32 v104, v241, v104
	ds_bpermute_b32 v105, v241, v105
	s_waitcnt lgkmcnt(0)
	global_store_dwordx2 v[112:113], v[104:105], off offset:128
	s_cbranch_execz .LBB0_499
	s_branch .LBB0_500

; DI unsigned pk2(float a, float b) { f32x2 v = {a, b}; bf2_t r = __builtin_convertvector(v, bf2_t); return __builtin_bit_cast(unsigned, r); }
; DI void epi_zo(const f32x4 (&acc)[2][2][4][2], unsigned char* O, const int esz, int wr, int wc, int fr, int fq) {
;     ...
;                 if (esz == 2) { u32x4 w; w[0] = pk2(v0[0], v0[1]); w[1] = pk2(v0[2], v0[3]); w[2] = pk2(v1[0], v1[1]); w[3] = pk2(v1[2], v1[3]); *(u32x4*)(rowp + bj * HALF * 2) = w; }
.LBB0_497:
	v_cvt_pk_bf16_f32 v108, v108, v109
	v_cvt_pk_bf16_f32 v109, v110, v111
	v_cvt_pk_bf16_f32 v110, v104, v105
	v_cvt_pk_bf16_f32 v111, v106, v107
	ds_bpermute_b32 v108, v241, v108
	ds_bpermute_b32 v109, v241, v109
	ds_bpermute_b32 v110, v241, v110
	ds_bpermute_b32 v111, v241, v111
	s_waitcnt lgkmcnt(0)
	global_store_dwordx4 v[112:113], v[108:111], off
	s_and_b64 vcc, exec, s[44:45]
	s_mov_b64 s[2:3], -1
	s_cbranch_vccz .LBB0_495

; DI unsigned pk2(float a, float b) { f32x2 v = {a, b}; bf2_t r = __builtin_convertvector(v, bf2_t); return __builtin_bit_cast(unsigned, r); }
; DI unsigned pk_fp8x4(float a, float b, float c, float d) { int w = __builtin_amdgcn_cvt_pk_fp8_f32(a, b, 0, false); w = __builtin_amdgcn_cvt_pk_fp8_f32(c, d, w, true); return (unsigned)w; }
; DI void epi_zo(const f32x4 (&acc)[2][2][4][2], unsigned char* O, const int esz, int wr, int wc, int fr, int fq) {
;     ...
;             unsigned char* rowp = O + ((size_t)(ai * HALF + wr * 64 + m * 16 + fr) * 2048 + wc * 32 + 8 * fq) * esz;
; #pragma unroll
;             for (int bj = 0; bj < 2; ++bj) {
;                 const f32x4 v0 = acc[ai][bj][m][0], v1 = acc[ai][bj][m][1];
;                 if (esz == 2) { u32x4 w; w[0] = pk2(v0[0], v0[1]); w[1] = pk2(v0[2], v0[3]); w[2] = pk2(v1[0], v1[1]); w[3] = pk2(v1[2], v1[3]); *(u32x4*)(rowp + bj * HALF * 2) = w; }
;                 else { u32x2 w; w[0] = pk_fp8x4(v0[0], v0[1], v0[2], v0[3]); w[1] = pk_fp8x4(v1[0], v1[1], v1[2], v1[3]); *(u32x2*)(rowp + bj * HALF) = w; }
.LBB0_499:
	v_cvt_pk_bf16_f32 v100, v100, v101
	v_cvt_pk_bf16_f32 v101, v102, v103
	v_cvt_pk_bf16_f32 v102, v96, v97
	v_cvt_pk_bf16_f32 v103, v98, v99
	ds_bpermute_b32 v100, v241, v100
	ds_bpermute_b32 v101, v241, v101
	ds_bpermute_b32 v102, v241, v102
	ds_bpermute_b32 v103, v241, v103
	s_waitcnt lgkmcnt(0)
	global_store_dwordx4 v[112:113], v[100:103], off offset:256
.LBB0_500:
	v_lshlrev_b64 v[96:97], v167, v[144:145]
	v_lshl_add_u64 v[96:97], v[160:161], 0, v[96:97]
	s_and_b64 vcc, exec, s[44:45]
	s_mov_b64 s[2:3], -1
	s_cbranch_vccnz .LBB0_504
	v_mov_b32_e32 v98, 0
	v_mov_b32_e32 v99, 0
	v_cvt_pk_fp8_f32 v98, v92, v93
	v_cvt_pk_fp8_f32 v99, v88, v89
	v_cvt_pk_fp8_f32 v98, v94, v95 op_sel:[0,0,1]
	v_cvt_pk_fp8_f32 v99, v90, v91 op_sel:[0,0,1]
	ds_bpermute_b32 v98, v241, v98
	ds_bpermute_b32 v99, v241, v99
	s_waitcnt lgkmcnt(0)
	global_store_dwordx2 v[96:97], v[98:99], off
	s_cbranch_execz .LBB0_505

; DI unsigned pk_fp8x4(float a, float b, float c, float d) { int w = __builtin_amdgcn_cvt_pk_fp8_f32(a, b, 0, false); w = __builtin_amdgcn_cvt_pk_fp8_f32(c, d, w, true); return (unsigned)w; }
; DI void epi_zo(const f32x4 (&acc)[2][2][4][2], unsigned char* O, const int esz, int wr, int wc, int fr, int fq) {
;     ...
;                 else { u32x2 w; w[0] = pk_fp8x4(v0[0], v0[1], v0[2], v0[3]); w[1] = pk_fp8x4(v1[0], v1[1], v1[2], v1[3]); *(u32x2*)(rowp + bj * HALF) = w; }
.LBB0_503:
	v_mov_b32_e32 v88, 0
	v_mov_b32_e32 v89, 0
	v_cvt_pk_fp8_f32 v88, v84, v85
	v_cvt_pk_fp8_f32 v89, v80, v81
	v_cvt_pk_fp8_f32 v88, v86, v87 op_sel:[0,0,1]
	v_cvt_pk_fp8_f32 v89, v82, v83 op_sel:[0,0,1]
	ds_bpermute_b32 v88, v241, v88
	ds_bpermute_b32 v89, v241, v89
	s_waitcnt lgkmcnt(0)
	global_store_dwordx2 v[96:97], v[88:89], off offset:128
	s_cbranch_execz .LBB0_507
	s_branch .LBB0_508

; DI unsigned pk2(float a, float b) { f32x2 v = {a, b}; bf2_t r = __builtin_convertvector(v, bf2_t); return __builtin_bit_cast(unsigned, r); }
; DI void epi_zo(const f32x4 (&acc)[2][2][4][2], unsigned char* O, const int esz, int wr, int wc, int fr, int fq) {
;     ...
;                 if (esz == 2) { u32x4 w; w[0] = pk2(v0[0], v0[1]); w[1] = pk2(v0[2], v0[3]); w[2] = pk2(v1[0], v1[1]); w[3] = pk2(v1[2], v1[3]); *(u32x4*)(rowp + bj * HALF * 2) = w; }
.LBB0_505:
	v_cvt_pk_bf16_f32 v92, v92, v93
	v_cvt_pk_bf16_f32 v93, v94, v95
	v_cvt_pk_bf16_f32 v94, v88, v89
	v_cvt_pk_bf16_f32 v95, v90, v91
	ds_bpermute_b32 v92, v241, v92
	ds_bpermute_b32 v93, v241, v93
	ds_bpermute_b32 v94, v241, v94
	ds_bpermute_b32 v95, v241, v95
	s_waitcnt lgkmcnt(0)
	global_store_dwordx4 v[96:97], v[92:95], off
	s_and_b64 vcc, exec, s[44:45]
	s_mov_b64 s[2:3], -1
	s_cbranch_vccz .LBB0_503

; DI unsigned pk2(float a, float b) { f32x2 v = {a, b}; bf2_t r = __builtin_convertvector(v, bf2_t); return __builtin_bit_cast(unsigned, r); }
; DI unsigned pk_fp8x4(float a, float b, float c, float d) { int w = __builtin_amdgcn_cvt_pk_fp8_f32(a, b, 0, false); w = __builtin_amdgcn_cvt_pk_fp8_f32(c, d, w, true); return (unsigned)w; }
; DI void epi_zo(const f32x4 (&acc)[2][2][4][2], unsigned char* O, const int esz, int wr, int wc, int fr, int fq) {
;     ...
;             unsigned char* rowp = O + ((size_t)(ai * HALF + wr * 64 + m * 16 + fr) * 2048 + wc * 32 + 8 * fq) * esz;
; #pragma unroll
;             for (int bj = 0; bj < 2; ++bj) {
;                 const f32x4 v0 = acc[ai][bj][m][0], v1 = acc[ai][bj][m][1];
;                 if (esz == 2) { u32x4 w; w[0] = pk2(v0[0], v0[1]); w[1] = pk2(v0[2], v0[3]); w[2] = pk2(v1[0], v1[1]); w[3] = pk2(v1[2], v1[3]); *(u32x4*)(rowp + bj * HALF * 2) = w; }
;                 else { u32x2 w; w[0] = pk_fp8x4(v0[0], v0[1], v0[2], v0[3]); w[1] = pk_fp8x4(v1[0], v1[1], v1[2], v1[3]); *(u32x2*)(rowp + bj * HALF) = w; }
.LBB0_507:
	v_cvt_pk_bf16_f32 v84, v84, v85
	v_cvt_pk_bf16_f32 v85, v86, v87
	v_cvt_pk_bf16_f32 v86, v80, v81
	v_cvt_pk_bf16_f32 v87, v82, v83
	ds_bpermute_b32 v84, v241, v84
	ds_bpermute_b32 v85, v241, v85
	ds_bpermute_b32 v86, v241, v86
	ds_bpermute_b32 v87, v241, v87
	s_waitcnt lgkmcnt(0)
	global_store_dwordx4 v[96:97], v[84:87], off offset:256
.LBB0_508:
	v_lshlrev_b64 v[80:81], v167, v[146:147]
	v_lshl_add_u64 v[80:81], v[160:161], 0, v[80:81]
	s_and_b64 vcc, exec, s[44:45]
	s_mov_b64 s[2:3], -1
	s_cbranch_vccnz .LBB0_512
	v_mov_b32_e32 v82, 0
	v_mov_b32_e32 v83, 0
	v_cvt_pk_fp8_f32 v82, v76, v77
	v_cvt_pk_fp8_f32 v83, v72, v73
	v_cvt_pk_fp8_f32 v82, v78, v79 op_sel:[0,0,1]
	v_cvt_pk_fp8_f32 v83, v74, v75 op_sel:[0,0,1]
	ds_bpermute_b32 v82, v241, v82
	ds_bpermute_b32 v83, v241, v83
	s_waitcnt lgkmcnt(0)
	global_store_dwordx2 v[80:81], v[82:83], off
	s_cbranch_execz .LBB0_513

; DI unsigned pk_fp8x4(float a, float b, float c, float d) { int w = __builtin_amdgcn_cvt_pk_fp8_f32(a, b, 0, false); w = __builtin_amdgcn_cvt_pk_fp8_f32(c, d, w, true); return (unsigned)w; }
; DI void epi_zo(const f32x4 (&acc)[2][2][4][2], unsigned char* O, const int esz, int wr, int wc, int fr, int fq) {
;     ...
;                 else { u32x2 w; w[0] = pk_fp8x4(v0[0], v0[1], v0[2], v0[3]); w[1] = pk_fp8x4(v1[0], v1[1], v1[2], v1[3]); *(u32x2*)(rowp + bj * HALF) = w; }
.LBB0_511:
	v_mov_b32_e32 v72, 0
	v_mov_b32_e32 v73, 0
	v_cvt_pk_fp8_f32 v72, v68, v69
	v_cvt_pk_fp8_f32 v73, v64, v65
	v_cvt_pk_fp8_f32 v72, v70, v71 op_sel:[0,0,1]
	v_cvt_pk_fp8_f32 v73, v66, v67 op_sel:[0,0,1]
	ds_bpermute_b32 v72, v241, v72
	ds_bpermute_b32 v73, v241, v73
	s_waitcnt lgkmcnt(0)
	global_store_dwordx2 v[80:81], v[72:73], off offset:128
	s_cbranch_execz .LBB0_515
	s_branch .LBB0_516

; DI unsigned pk2(float a, float b) { f32x2 v = {a, b}; bf2_t r = __builtin_convertvector(v, bf2_t); return __builtin_bit_cast(unsigned, r); }
; DI void epi_zo(const f32x4 (&acc)[2][2][4][2], unsigned char* O, const int esz, int wr, int wc, int fr, int fq) {
;     ...
;                 if (esz == 2) { u32x4 w; w[0] = pk2(v0[0], v0[1]); w[1] = pk2(v0[2], v0[3]); w[2] = pk2(v1[0], v1[1]); w[3] = pk2(v1[2], v1[3]); *(u32x4*)(rowp + bj * HALF * 2) = w; }
.LBB0_513:
	v_cvt_pk_bf16_f32 v76, v76, v77
	v_cvt_pk_bf16_f32 v77, v78, v79
	v_cvt_pk_bf16_f32 v78, v72, v73
	v_cvt_pk_bf16_f32 v79, v74, v75
	ds_bpermute_b32 v76, v241, v76
	ds_bpermute_b32 v77, v241, v77
	ds_bpermute_b32 v78, v241, v78
	ds_bpermute_b32 v79, v241, v79
	s_waitcnt lgkmcnt(0)
	global_store_dwordx4 v[80:81], v[76:79], off
	s_and_b64 vcc, exec, s[44:45]
	s_mov_b64 s[2:3], -1
	s_cbranch_vccz .LBB0_511

; DI unsigned pk2(float a, float b) { f32x2 v = {a, b}; bf2_t r = __builtin_convertvector(v, bf2_t); return __builtin_bit_cast(unsigned, r); }
; DI unsigned pk_fp8x4(float a, float b, float c, float d) { int w = __builtin_amdgcn_cvt_pk_fp8_f32(a, b, 0, false); w = __builtin_amdgcn_cvt_pk_fp8_f32(c, d, w, true); return (unsigned)w; }
; DI void epi_zo(const f32x4 (&acc)[2][2][4][2], unsigned char* O, const int esz, int wr, int wc, int fr, int fq) {
;     ...
;             unsigned char* rowp = O + ((size_t)(ai * HALF + wr * 64 + m * 16 + fr) * 2048 + wc * 32 + 8 * fq) * esz;
; #pragma unroll
;             for (int bj = 0; bj < 2; ++bj) {
;                 const f32x4 v0 = acc[ai][bj][m][0], v1 = acc[ai][bj][m][1];
;                 if (esz == 2) { u32x4 w; w[0] = pk2(v0[0], v0[1]); w[1] = pk2(v0[2], v0[3]); w[2] = pk2(v1[0], v1[1]); w[3] = pk2(v1[2], v1[3]); *(u32x4*)(rowp + bj * HALF * 2) = w; }
;                 else { u32x2 w; w[0] = pk_fp8x4(v0[0], v0[1], v0[2], v0[3]); w[1] = pk_fp8x4(v1[0], v1[1], v1[2], v1[3]); *(u32x2*)(rowp + bj * HALF) = w; }
.LBB0_515:
	v_cvt_pk_bf16_f32 v68, v68, v69
	v_cvt_pk_bf16_f32 v69, v70, v71
	v_cvt_pk_bf16_f32 v70, v64, v65
	v_cvt_pk_bf16_f32 v71, v66, v67
	ds_bpermute_b32 v68, v241, v68
	ds_bpermute_b32 v69, v241, v69
	ds_bpermute_b32 v70, v241, v70
	ds_bpermute_b32 v71, v241, v71
	s_waitcnt lgkmcnt(0)
	global_store_dwordx4 v[80:81], v[68:71], off offset:256
.LBB0_516:
	v_lshlrev_b64 v[64:65], v167, v[148:149]
	v_lshl_add_u64 v[64:65], v[160:161], 0, v[64:65]
	s_and_b64 vcc, exec, s[44:45]
	s_mov_b64 s[2:3], -1
	s_cbranch_vccnz .LBB0_520
	v_mov_b32_e32 v66, 0
	v_mov_b32_e32 v67, 0
	v_cvt_pk_fp8_f32 v66, v60, v61
	v_cvt_pk_fp8_f32 v67, v56, v57
	v_cvt_pk_fp8_f32 v66, v62, v63 op_sel:[0,0,1]
	v_cvt_pk_fp8_f32 v67, v58, v59 op_sel:[0,0,1]
	ds_bpermute_b32 v66, v241, v66
	ds_bpermute_b32 v67, v241, v67
	s_waitcnt lgkmcnt(0)
	global_store_dwordx2 v[64:65], v[66:67], off
	s_cbranch_execz .LBB0_521

; DI unsigned pk_fp8x4(float a, float b, float c, float d) { int w = __builtin_amdgcn_cvt_pk_fp8_f32(a, b, 0, false); w = __builtin_amdgcn_cvt_pk_fp8_f32(c, d, w, true); return (unsigned)w; }
; DI void epi_zo(const f32x4 (&acc)[2][2][4][2], unsigned char* O, const int esz, int wr, int wc, int fr, int fq) {
;     ...
;                 else { u32x2 w; w[0] = pk_fp8x4(v0[0], v0[1], v0[2], v0[3]); w[1] = pk_fp8x4(v1[0], v1[1], v1[2], v1[3]); *(u32x2*)(rowp + bj * HALF) = w; }
.LBB0_519:
	v_mov_b32_e32 v56, 0
	v_mov_b32_e32 v57, 0
	v_cvt_pk_fp8_f32 v56, v52, v53
	v_cvt_pk_fp8_f32 v57, v48, v49
	v_cvt_pk_fp8_f32 v56, v54, v55 op_sel:[0,0,1]
	v_cvt_pk_fp8_f32 v57, v50, v51 op_sel:[0,0,1]
	ds_bpermute_b32 v56, v241, v56
	ds_bpermute_b32 v57, v241, v57
	s_waitcnt lgkmcnt(0)
	global_store_dwordx2 v[64:65], v[56:57], off offset:128
	s_cbranch_execz .LBB0_523
	s_branch .LBB0_524

; DI unsigned pk2(float a, float b) { f32x2 v = {a, b}; bf2_t r = __builtin_convertvector(v, bf2_t); return __builtin_bit_cast(unsigned, r); }
; DI void epi_zo(const f32x4 (&acc)[2][2][4][2], unsigned char* O, const int esz, int wr, int wc, int fr, int fq) {
;     ...
;                 if (esz == 2) { u32x4 w; w[0] = pk2(v0[0], v0[1]); w[1] = pk2(v0[2], v0[3]); w[2] = pk2(v1[0], v1[1]); w[3] = pk2(v1[2], v1[3]); *(u32x4*)(rowp + bj * HALF * 2) = w; }
.LBB0_521:
	v_cvt_pk_bf16_f32 v60, v60, v61
	v_cvt_pk_bf16_f32 v61, v62, v63
	v_cvt_pk_bf16_f32 v62, v56, v57
	v_cvt_pk_bf16_f32 v63, v58, v59
	ds_bpermute_b32 v60, v241, v60
	ds_bpermute_b32 v61, v241, v61
	ds_bpermute_b32 v62, v241, v62
	ds_bpermute_b32 v63, v241, v63
	s_waitcnt lgkmcnt(0)
	global_store_dwordx4 v[64:65], v[60:63], off
	s_and_b64 vcc, exec, s[44:45]
	s_mov_b64 s[2:3], -1
	s_cbranch_vccz .LBB0_519

; DI unsigned pk2(float a, float b) { f32x2 v = {a, b}; bf2_t r = __builtin_convertvector(v, bf2_t); return __builtin_bit_cast(unsigned, r); }
; DI unsigned pk_fp8x4(float a, float b, float c, float d) { int w = __builtin_amdgcn_cvt_pk_fp8_f32(a, b, 0, false); w = __builtin_amdgcn_cvt_pk_fp8_f32(c, d, w, true); return (unsigned)w; }
; DI void epi_zo(const f32x4 (&acc)[2][2][4][2], unsigned char* O, const int esz, int wr, int wc, int fr, int fq) {
;     ...
;             unsigned char* rowp = O + ((size_t)(ai * HALF + wr * 64 + m * 16 + fr) * 2048 + wc * 32 + 8 * fq) * esz;
; #pragma unroll
;             for (int bj = 0; bj < 2; ++bj) {
;                 const f32x4 v0 = acc[ai][bj][m][0], v1 = acc[ai][bj][m][1];
;                 if (esz == 2) { u32x4 w; w[0] = pk2(v0[0], v0[1]); w[1] = pk2(v0[2], v0[3]); w[2] = pk2(v1[0], v1[1]); w[3] = pk2(v1[2], v1[3]); *(u32x4*)(rowp + bj * HALF * 2) = w; }
;                 else { u32x2 w; w[0] = pk_fp8x4(v0[0], v0[1], v0[2], v0[3]); w[1] = pk_fp8x4(v1[0], v1[1], v1[2], v1[3]); *(u32x2*)(rowp + bj * HALF) = w; }
.LBB0_523:
	v_cvt_pk_bf16_f32 v52, v52, v53
	v_cvt_pk_bf16_f32 v53, v54, v55
	v_cvt_pk_bf16_f32 v54, v48, v49
	v_cvt_pk_bf16_f32 v55, v50, v51
	ds_bpermute_b32 v52, v241, v52
	ds_bpermute_b32 v53, v241, v53
	ds_bpermute_b32 v54, v241, v54
	ds_bpermute_b32 v55, v241, v55
	s_waitcnt lgkmcnt(0)
	global_store_dwordx4 v[64:65], v[52:55], off offset:256
.LBB0_524:
	v_lshlrev_b64 v[48:49], v167, v[150:151]
	v_lshl_add_u64 v[48:49], v[160:161], 0, v[48:49]
	s_and_b64 vcc, exec, s[44:45]
	s_mov_b64 s[2:3], -1
	s_cbranch_vccnz .LBB0_528
	v_mov_b32_e32 v50, 0
	v_mov_b32_e32 v51, 0
	v_cvt_pk_fp8_f32 v50, v44, v45
	v_cvt_pk_fp8_f32 v51, v40, v41
	v_cvt_pk_fp8_f32 v50, v46, v47 op_sel:[0,0,1]
	v_cvt_pk_fp8_f32 v51, v42, v43 op_sel:[0,0,1]
	ds_bpermute_b32 v50, v241, v50
	ds_bpermute_b32 v51, v241, v51
	s_waitcnt lgkmcnt(0)
	global_store_dwordx2 v[48:49], v[50:51], off
	s_cbranch_execz .LBB0_529

; DI unsigned pk_fp8x4(float a, float b, float c, float d) { int w = __builtin_amdgcn_cvt_pk_fp8_f32(a, b, 0, false); w = __builtin_amdgcn_cvt_pk_fp8_f32(c, d, w, true); return (unsigned)w; }
; DI void epi_zo(const f32x4 (&acc)[2][2][4][2], unsigned char* O, const int esz, int wr, int wc, int fr, int fq) {
;     ...
;                 else { u32x2 w; w[0] = pk_fp8x4(v0[0], v0[1], v0[2], v0[3]); w[1] = pk_fp8x4(v1[0], v1[1], v1[2], v1[3]); *(u32x2*)(rowp + bj * HALF) = w; }
.LBB0_527:
	v_mov_b32_e32 v40, 0
	v_mov_b32_e32 v41, 0
	v_cvt_pk_fp8_f32 v40, v36, v37
	v_cvt_pk_fp8_f32 v41, v32, v33
	v_cvt_pk_fp8_f32 v40, v38, v39 op_sel:[0,0,1]
	v_cvt_pk_fp8_f32 v41, v34, v35 op_sel:[0,0,1]
	ds_bpermute_b32 v40, v241, v40
	ds_bpermute_b32 v41, v241, v41
	s_waitcnt lgkmcnt(0)
	global_store_dwordx2 v[48:49], v[40:41], off offset:128
	s_cbranch_execz .LBB0_531
	s_branch .LBB0_532

; DI unsigned pk2(float a, float b) { f32x2 v = {a, b}; bf2_t r = __builtin_convertvector(v, bf2_t); return __builtin_bit_cast(unsigned, r); }
; DI void epi_zo(const f32x4 (&acc)[2][2][4][2], unsigned char* O, const int esz, int wr, int wc, int fr, int fq) {
;     ...
;                 if (esz == 2) { u32x4 w; w[0] = pk2(v0[0], v0[1]); w[1] = pk2(v0[2], v0[3]); w[2] = pk2(v1[0], v1[1]); w[3] = pk2(v1[2], v1[3]); *(u32x4*)(rowp + bj * HALF * 2) = w; }
.LBB0_529:
	v_cvt_pk_bf16_f32 v44, v44, v45
	v_cvt_pk_bf16_f32 v45, v46, v47
	v_cvt_pk_bf16_f32 v46, v40, v41
	v_cvt_pk_bf16_f32 v47, v42, v43
	ds_bpermute_b32 v44, v241, v44
	ds_bpermute_b32 v45, v241, v45
	ds_bpermute_b32 v46, v241, v46
	ds_bpermute_b32 v47, v241, v47
	s_waitcnt lgkmcnt(0)
	global_store_dwordx4 v[48:49], v[44:47], off
	s_and_b64 vcc, exec, s[44:45]
	s_mov_b64 s[2:3], -1
	s_cbranch_vccz .LBB0_527

; DI unsigned pk2(float a, float b) { f32x2 v = {a, b}; bf2_t r = __builtin_convertvector(v, bf2_t); return __builtin_bit_cast(unsigned, r); }
; DI unsigned pk_fp8x4(float a, float b, float c, float d) { int w = __builtin_amdgcn_cvt_pk_fp8_f32(a, b, 0, false); w = __builtin_amdgcn_cvt_pk_fp8_f32(c, d, w, true); return (unsigned)w; }
; DI void epi_zo(const f32x4 (&acc)[2][2][4][2], unsigned char* O, const int esz, int wr, int wc, int fr, int fq) {
;     ...
;             unsigned char* rowp = O + ((size_t)(ai * HALF + wr * 64 + m * 16 + fr) * 2048 + wc * 32 + 8 * fq) * esz;
; #pragma unroll
;             for (int bj = 0; bj < 2; ++bj) {
;                 const f32x4 v0 = acc[ai][bj][m][0], v1 = acc[ai][bj][m][1];
;                 if (esz == 2) { u32x4 w; w[0] = pk2(v0[0], v0[1]); w[1] = pk2(v0[2], v0[3]); w[2] = pk2(v1[0], v1[1]); w[3] = pk2(v1[2], v1[3]); *(u32x4*)(rowp + bj * HALF * 2) = w; }
;                 else { u32x2 w; w[0] = pk_fp8x4(v0[0], v0[1], v0[2], v0[3]); w[1] = pk_fp8x4(v1[0], v1[1], v1[2], v1[3]); *(u32x2*)(rowp + bj * HALF) = w; }
.LBB0_531:
	v_cvt_pk_bf16_f32 v36, v36, v37
	v_cvt_pk_bf16_f32 v37, v38, v39
	v_cvt_pk_bf16_f32 v38, v32, v33
	v_cvt_pk_bf16_f32 v39, v34, v35
	ds_bpermute_b32 v36, v241, v36
	ds_bpermute_b32 v37, v241, v37
	ds_bpermute_b32 v38, v241, v38
	ds_bpermute_b32 v39, v241, v39
	s_waitcnt lgkmcnt(0)
	global_store_dwordx4 v[48:49], v[36:39], off offset:256
.LBB0_532:
	v_lshlrev_b64 v[32:33], v167, v[152:153]
	v_lshl_add_u64 v[32:33], v[160:161], 0, v[32:33]
	s_and_b64 vcc, exec, s[44:45]
	s_mov_b64 s[2:3], -1
	s_cbranch_vccnz .LBB0_536
	v_mov_b32_e32 v34, 0
	v_mov_b32_e32 v35, 0
	v_cvt_pk_fp8_f32 v34, v28, v29
	v_cvt_pk_fp8_f32 v35, v24, v25
	v_cvt_pk_fp8_f32 v34, v30, v31 op_sel:[0,0,1]
	v_cvt_pk_fp8_f32 v35, v26, v27 op_sel:[0,0,1]
	ds_bpermute_b32 v34, v241, v34
	ds_bpermute_b32 v35, v241, v35
	s_waitcnt lgkmcnt(0)
	global_store_dwordx2 v[32:33], v[34:35], off
	s_cbranch_execz .LBB0_537

; DI unsigned pk_fp8x4(float a, float b, float c, float d) { int w = __builtin_amdgcn_cvt_pk_fp8_f32(a, b, 0, false); w = __builtin_amdgcn_cvt_pk_fp8_f32(c, d, w, true); return (unsigned)w; }
; DI void epi_zo(const f32x4 (&acc)[2][2][4][2], unsigned char* O, const int esz, int wr, int wc, int fr, int fq) {
;     ...
;                 else { u32x2 w; w[0] = pk_fp8x4(v0[0], v0[1], v0[2], v0[3]); w[1] = pk_fp8x4(v1[0], v1[1], v1[2], v1[3]); *(u32x2*)(rowp + bj * HALF) = w; }
.LBB0_535:
	v_mov_b32_e32 v24, 0
	v_mov_b32_e32 v25, 0
	v_cvt_pk_fp8_f32 v24, v20, v21
	v_cvt_pk_fp8_f32 v25, v16, v17
	v_cvt_pk_fp8_f32 v24, v22, v23 op_sel:[0,0,1]
	v_cvt_pk_fp8_f32 v25, v18, v19 op_sel:[0,0,1]
	ds_bpermute_b32 v24, v241, v24
	ds_bpermute_b32 v25, v241, v25
	s_waitcnt lgkmcnt(0)
	global_store_dwordx2 v[32:33], v[24:25], off offset:128
	s_cbranch_execz .LBB0_539
	s_branch .LBB0_540

; DI unsigned pk2(float a, float b) { f32x2 v = {a, b}; bf2_t r = __builtin_convertvector(v, bf2_t); return __builtin_bit_cast(unsigned, r); }
; DI void epi_zo(const f32x4 (&acc)[2][2][4][2], unsigned char* O, const int esz, int wr, int wc, int fr, int fq) {
;     ...
;                 if (esz == 2) { u32x4 w; w[0] = pk2(v0[0], v0[1]); w[1] = pk2(v0[2], v0[3]); w[2] = pk2(v1[0], v1[1]); w[3] = pk2(v1[2], v1[3]); *(u32x4*)(rowp + bj * HALF * 2) = w; }
.LBB0_537:
	v_cvt_pk_bf16_f32 v28, v28, v29
	v_cvt_pk_bf16_f32 v29, v30, v31
	v_cvt_pk_bf16_f32 v30, v24, v25
	v_cvt_pk_bf16_f32 v31, v26, v27
	ds_bpermute_b32 v28, v241, v28
	ds_bpermute_b32 v29, v241, v29
	ds_bpermute_b32 v30, v241, v30
	ds_bpermute_b32 v31, v241, v31
	s_waitcnt lgkmcnt(0)
	global_store_dwordx4 v[32:33], v[28:31], off
	s_and_b64 vcc, exec, s[44:45]
	s_mov_b64 s[2:3], -1
	s_cbranch_vccz .LBB0_535

; DI unsigned pk2(float a, float b) { f32x2 v = {a, b}; bf2_t r = __builtin_convertvector(v, bf2_t); return __builtin_bit_cast(unsigned, r); }
; DI unsigned pk_fp8x4(float a, float b, float c, float d) { int w = __builtin_amdgcn_cvt_pk_fp8_f32(a, b, 0, false); w = __builtin_amdgcn_cvt_pk_fp8_f32(c, d, w, true); return (unsigned)w; }
; DI void epi_zo(const f32x4 (&acc)[2][2][4][2], unsigned char* O, const int esz, int wr, int wc, int fr, int fq) {
;     ...
;             unsigned char* rowp = O + ((size_t)(ai * HALF + wr * 64 + m * 16 + fr) * 2048 + wc * 32 + 8 * fq) * esz;
; #pragma unroll
;             for (int bj = 0; bj < 2; ++bj) {
;                 const f32x4 v0 = acc[ai][bj][m][0], v1 = acc[ai][bj][m][1];
;                 if (esz == 2) { u32x4 w; w[0] = pk2(v0[0], v0[1]); w[1] = pk2(v0[2], v0[3]); w[2] = pk2(v1[0], v1[1]); w[3] = pk2(v1[2], v1[3]); *(u32x4*)(rowp + bj * HALF * 2) = w; }
;                 else { u32x2 w; w[0] = pk_fp8x4(v0[0], v0[1], v0[2], v0[3]); w[1] = pk_fp8x4(v1[0], v1[1], v1[2], v1[3]); *(u32x2*)(rowp + bj * HALF) = w; }
.LBB0_539:
	v_cvt_pk_bf16_f32 v20, v20, v21
	v_cvt_pk_bf16_f32 v21, v22, v23
	v_cvt_pk_bf16_f32 v22, v16, v17
	v_cvt_pk_bf16_f32 v23, v18, v19
	ds_bpermute_b32 v20, v241, v20
	ds_bpermute_b32 v21, v241, v21
	ds_bpermute_b32 v22, v241, v22
	ds_bpermute_b32 v23, v241, v23
	s_waitcnt lgkmcnt(0)
	global_store_dwordx4 v[32:33], v[20:23], off offset:256
.LBB0_540:
	v_lshlrev_b64 v[16:17], v167, v[154:155]
	v_lshl_add_u64 v[16:17], v[160:161], 0, v[16:17]
	s_and_b64 vcc, exec, s[44:45]
	s_mov_b64 s[2:3], -1
	s_cbranch_vccnz .LBB0_544
	v_mov_b32_e32 v18, 0
	v_mov_b32_e32 v19, 0
	v_cvt_pk_fp8_f32 v18, v12, v13
	v_cvt_pk_fp8_f32 v19, v8, v9
	v_cvt_pk_fp8_f32 v18, v14, v15 op_sel:[0,0,1]
	v_cvt_pk_fp8_f32 v19, v10, v11 op_sel:[0,0,1]
	ds_bpermute_b32 v18, v241, v18
	ds_bpermute_b32 v19, v241, v19
	s_waitcnt lgkmcnt(0)
	global_store_dwordx2 v[16:17], v[18:19], off
	s_cbranch_execz .LBB0_545

; DI unsigned pk_fp8x4(float a, float b, float c, float d) { int w = __builtin_amdgcn_cvt_pk_fp8_f32(a, b, 0, false); w = __builtin_amdgcn_cvt_pk_fp8_f32(c, d, w, true); return (unsigned)w; }
; DI void epi_zo(const f32x4 (&acc)[2][2][4][2], unsigned char* O, const int esz, int wr, int wc, int fr, int fq) {
;     ...
;                 else { u32x2 w; w[0] = pk_fp8x4(v0[0], v0[1], v0[2], v0[3]); w[1] = pk_fp8x4(v1[0], v1[1], v1[2], v1[3]); *(u32x2*)(rowp + bj * HALF) = w; }
.LBB0_543:
	v_mov_b32_e32 v8, 0
	v_mov_b32_e32 v9, 0
	v_cvt_pk_fp8_f32 v8, v4, v5
	v_cvt_pk_fp8_f32 v9, v0, v1
	v_cvt_pk_fp8_f32 v8, v6, v7 op_sel:[0,0,1]
	v_cvt_pk_fp8_f32 v9, v2, v3 op_sel:[0,0,1]
	ds_bpermute_b32 v8, v241, v8
	ds_bpermute_b32 v9, v241, v9
	s_waitcnt lgkmcnt(0)
	global_store_dwordx2 v[16:17], v[8:9], off offset:128
	s_cbranch_execnz .LBB0_479
	s_branch .LBB0_547

; DI unsigned pk2(float a, float b) { f32x2 v = {a, b}; bf2_t r = __builtin_convertvector(v, bf2_t); return __builtin_bit_cast(unsigned, r); }
; DI void epi_zo(const f32x4 (&acc)[2][2][4][2], unsigned char* O, const int esz, int wr, int wc, int fr, int fq) {
;     ...
;                 if (esz == 2) { u32x4 w; w[0] = pk2(v0[0], v0[1]); w[1] = pk2(v0[2], v0[3]); w[2] = pk2(v1[0], v1[1]); w[3] = pk2(v1[2], v1[3]); *(u32x4*)(rowp + bj * HALF * 2) = w; }
.LBB0_545:
	v_cvt_pk_bf16_f32 v12, v12, v13
	v_cvt_pk_bf16_f32 v13, v14, v15
	v_cvt_pk_bf16_f32 v14, v8, v9
	v_cvt_pk_bf16_f32 v15, v10, v11
	ds_bpermute_b32 v12, v241, v12
	ds_bpermute_b32 v13, v241, v13
	ds_bpermute_b32 v14, v241, v14
	ds_bpermute_b32 v15, v241, v15
	s_waitcnt lgkmcnt(0)
	global_store_dwordx4 v[16:17], v[12:15], off
	s_and_b64 vcc, exec, s[44:45]
	s_mov_b64 s[2:3], -1
	s_cbranch_vccz .LBB0_543

; DI unsigned pk2(float a, float b) { f32x2 v = {a, b}; bf2_t r = __builtin_convertvector(v, bf2_t); return __builtin_bit_cast(unsigned, r); }
; DI void epi_zo(const f32x4 (&acc)[2][2][4][2], unsigned char* O, const int esz, int wr, int wc, int fr, int fq) {
;     ...
;                 if (esz == 2) { u32x4 w; w[0] = pk2(v0[0], v0[1]); w[1] = pk2(v0[2], v0[3]); w[2] = pk2(v1[0], v1[1]); w[3] = pk2(v1[2], v1[3]); *(u32x4*)(rowp + bj * HALF * 2) = w; }
.LBB0_547:
	v_cvt_pk_bf16_f32 v4, v4, v5
	v_cvt_pk_bf16_f32 v5, v6, v7
	v_cvt_pk_bf16_f32 v6, v0, v1
	v_cvt_pk_bf16_f32 v7, v2, v3
	ds_bpermute_b32 v4, v241, v4
	ds_bpermute_b32 v5, v241, v5
	ds_bpermute_b32 v6, v241, v6
	ds_bpermute_b32 v7, v241, v7
	s_waitcnt lgkmcnt(0)
	global_store_dwordx4 v[16:17], v[4:7], off offset:256
	s_branch .LBB0_479
